# GEMM K-loop: 12 duplicate lgkmcnt waits removed, plus grid-barrier poll loads issued together, on top of the GEMM static-priority version
# speedup vs baseline: 1.0052x; 1.0052x over previous
; #define LDA(dst, b, h) _Pragma("unroll") for (int m = 0; m < 4; ++m) _Pragma("unroll") for (int k = 0; k < 2; ++k) \
;     dst[m][k] = *reinterpret_cast<const bf16x8*>((char*)SA(b, h) + lds_byte(wr * 64 + m * 16 + fr, k * 32 + fq * 8))
; #define LDB(dst, b, h) _Pragma("unroll") for (int n = 0; n < 2; ++n) _Pragma("unroll") for (int k = 0; k < 2; ++k) \
;     dst[n][k] = *reinterpret_cast<const bf16x8*>((char*)SB(b, h) + lds_byte(wc * 32 + n * 16 + fr, k * 32 + fq * 8))
; #define MMA(ai, bj, At_, Bt_) do { __builtin_amdgcn_s_setprio(1); \
;     _Pragma("unroll") for (int m = 0; m < 4; ++m) _Pragma("unroll") for (int n = 0; n < 2; ++n) _Pragma("unroll") for (int k = 0; k < 2; ++k) \
;       acc[ai][bj][m][n] = __builtin_amdgcn_mfma_f32_16x16x32_bf16(At_[m][k], Bt_[n][k], acc[ai][bj][m][n], 0, 0, 0); \
;     __builtin_amdgcn_s_setprio(0); } while (0)
; #define WAIT_V(n) asm volatile("s_waitcnt vmcnt(" #n ")" ::: "memory")
; #define WAIT_L(n) asm volatile("s_waitcnt lgkmcnt(" #n ")" ::: "memory")
; #define BAR __builtin_amdgcn_s_barrier()
; #define SCHED __builtin_amdgcn_sched_barrier(0)
; DI void gemm_tile(const GD& g, int pm, int pn, bf16_t* shm) {
;     ...
;   for (int t = 0; t < nt - 2; t += 2) {
;     LDB(B0, 0, 0); SCHED; LDA(At, 0, 0); STAGE(SA(1, 1), A, lda, brow + HALF, t + 1);
;     WAIT_L(8); BAR; WAIT_L(0); MMA(0, 0, At, B0); BAR; SCHED;
;     LDB(B1, 0, 1); STAGE(SB(0, 0), Bt, ldb, bh0, t + 2);
;     BAR; WAIT_L(0); MMA(0, 1, At, B1); BAR;
;     LDA(At, 0, 1); STAGE(SA(0, 0), A, lda, brow, t + 2);
;     BAR; WAIT_L(0); MMA(1, 0, At, B0); BAR; SCHED;
;     STAGE(SB(0, 1), Bt, ldb, bh1, t + 2);
;     WAIT_V(6); BAR; MMA(1, 1, At, B1); BAR;
.Lgprio_skip:
.LBB0_460:
	ds_read_b128 v[154:157], v147
	ds_read_b128 v[158:161], v147 offset:1024
	ds_read_b128 v[162:165], v147 offset:2048
	ds_read_b128 v[166:169], v147 offset:3072
	s_add_u32 s67, s41, 0xffffff00
	s_addc_u32 s97, s63, -1
	s_add_u32 s82, s67, s6
	s_addc_u32 s83, s97, s7
	s_add_i32 m0, s70, 0xc000
	v_lshl_add_u64 v[202:203], s[82:83], 0, v[0:1]
	s_add_u32 s82, s67, s8
	v_add_u32_e32 v237, v146, v142
	s_addc_u32 s83, s97, s9
	ds_read_b128 v[170:173], v237
	ds_read_b128 v[174:177], v237 offset:1024
	ds_read_b128 v[178:181], v148
	ds_read_b128 v[182:185], v148 offset:1024
	ds_read_b128 v[186:189], v149
	ds_read_b128 v[190:193], v149 offset:1024
	ds_read_b128 v[194:197], v150
	ds_read_b128 v[198:201], v150 offset:1024
	global_load_lds_dwordx4 v[202:203], off
	v_lshl_add_u64 v[202:203], s[82:83], 0, v[0:1]
	s_add_i32 m0, s70, 0xe000
	s_nop 0
	global_load_lds_dwordx4 v[202:203], off
	s_waitcnt lgkmcnt(8)
	s_barrier
	s_waitcnt lgkmcnt(0)
	v_mfma_f32_16x16x32_bf16 v[114:117], v[170:173], v[154:157], v[114:117]
	v_mfma_f32_16x16x32_bf16 v[126:129], v[170:173], v[162:165], v[126:129]
	v_mfma_f32_16x16x32_bf16 v[122:125], v[178:181], v[154:157], v[122:125]
	v_mfma_f32_16x16x32_bf16 v[118:121], v[178:181], v[162:165], v[118:121]
	v_mfma_f32_16x16x32_bf16 v[110:113], v[186:189], v[154:157], v[110:113]
	v_mfma_f32_16x16x32_bf16 v[106:109], v[186:189], v[162:165], v[106:109]
	v_mfma_f32_16x16x32_bf16 v[102:105], v[194:197], v[154:157], v[102:105]
	v_mfma_f32_16x16x32_bf16 v[98:101], v[194:197], v[162:165], v[98:101]
	v_mfma_f32_16x16x32_bf16 v[114:117], v[174:177], v[158:161], v[114:117]
	v_mfma_f32_16x16x32_bf16 v[126:129], v[174:177], v[166:169], v[126:129]
	v_mfma_f32_16x16x32_bf16 v[122:125], v[182:185], v[158:161], v[122:125]
	v_mfma_f32_16x16x32_bf16 v[118:121], v[182:185], v[166:169], v[118:121]
	v_mfma_f32_16x16x32_bf16 v[110:113], v[190:193], v[158:161], v[110:113]
	v_mfma_f32_16x16x32_bf16 v[106:109], v[190:193], v[166:169], v[106:109]
	v_mfma_f32_16x16x32_bf16 v[102:105], v[198:201], v[158:161], v[102:105]
	v_mfma_f32_16x16x32_bf16 v[98:101], v[198:201], v[166:169], v[98:101]
	s_barrier
	s_add_i32 s3, s3, 2
	s_add_u32 s67, s58, 0xffffff80
	s_addc_u32 s97, s59, -1
	s_add_u32 s82, s67, s10
	s_addc_u32 s83, s97, s11
	v_lshl_add_u64 v[202:203], s[82:83], 0, v[0:1]
	s_add_u32 s82, s67, s12
	s_mov_b32 m0, s36
	s_addc_u32 s83, s97, s13
	ds_read_b128 v[238:241], v151
	ds_read_b128 v[242:245], v151 offset:1024
	ds_read_b128 v[246:249], v151 offset:2048
	ds_read_b128 v[214:217], v151 offset:3072
	global_load_lds_dwordx4 v[202:203], off
	v_lshl_add_u64 v[202:203], s[82:83], 0, v[0:1]
	s_mov_b32 m0, s66
	s_nop 0
	global_load_lds_dwordx4 v[202:203], off
	s_barrier
	s_waitcnt lgkmcnt(0)
	v_mfma_f32_16x16x32_bf16 v[94:97], v[170:173], v[238:241], v[94:97]
	v_mfma_f32_16x16x32_bf16 v[90:93], v[170:173], v[246:249], v[90:93]
	v_mfma_f32_16x16x32_bf16 v[86:89], v[178:181], v[238:241], v[86:89]
	v_mfma_f32_16x16x32_bf16 v[82:85], v[178:181], v[246:249], v[82:85]
	v_mfma_f32_16x16x32_bf16 v[78:81], v[186:189], v[238:241], v[78:81]
	v_mfma_f32_16x16x32_bf16 v[74:77], v[186:189], v[246:249], v[74:77]
	v_mfma_f32_16x16x32_bf16 v[70:73], v[194:197], v[238:241], v[70:73]
	v_mfma_f32_16x16x32_bf16 v[66:69], v[194:197], v[246:249], v[66:69]
	v_mfma_f32_16x16x32_bf16 v[94:97], v[174:177], v[242:245], v[94:97]
	v_mfma_f32_16x16x32_bf16 v[90:93], v[174:177], v[214:217], v[90:93]
	v_mfma_f32_16x16x32_bf16 v[86:89], v[182:185], v[242:245], v[86:89]
	v_mfma_f32_16x16x32_bf16 v[82:85], v[182:185], v[214:217], v[82:85]
	v_mfma_f32_16x16x32_bf16 v[78:81], v[190:193], v[242:245], v[78:81]
	v_mfma_f32_16x16x32_bf16 v[74:77], v[190:193], v[214:217], v[74:77]
	v_mfma_f32_16x16x32_bf16 v[70:73], v[198:201], v[242:245], v[70:73]
	v_mfma_f32_16x16x32_bf16 v[66:69], v[198:201], v[214:217], v[66:69]
	s_add_u32 vcc_lo, s41, 0xffffff80
	s_addc_u32 vcc_hi, s63, -1
	s_add_u32 s82, vcc_lo, s50
	s_addc_u32 s83, vcc_hi, s51
	v_lshl_add_u64 v[202:203], s[82:83], 0, v[0:1]
	s_add_u32 s82, vcc_lo, s52
	s_mov_b32 m0, s70
	s_addc_u32 s83, vcc_hi, s53
	s_barrier
	ds_read_b128 v[170:173], v237 offset:16384
	ds_read_b128 v[174:177], v237 offset:17408
	ds_read_b128 v[178:181], v148 offset:16384
	ds_read_b128 v[182:185], v148 offset:17408
	ds_read_b128 v[186:189], v149 offset:16384
	ds_read_b128 v[190:193], v149 offset:17408
	ds_read_b128 v[194:197], v150 offset:16384
	ds_read_b128 v[198:201], v150 offset:17408
	global_load_lds_dwordx4 v[202:203], off
	v_lshl_add_u64 v[202:203], s[82:83], 0, v[0:1]
	s_mov_b32 m0, s44
	s_nop 0
	global_load_lds_dwordx4 v[202:203], off
	s_barrier
	s_waitcnt lgkmcnt(0)
	v_mfma_f32_16x16x32_bf16 v[62:65], v[170:173], v[154:157], v[62:65]
	v_mfma_f32_16x16x32_bf16 v[58:61], v[170:173], v[162:165], v[58:61]
	v_mfma_f32_16x16x32_bf16 v[54:57], v[178:181], v[154:157], v[54:57]
	v_mfma_f32_16x16x32_bf16 v[50:53], v[178:181], v[162:165], v[50:53]
	v_mfma_f32_16x16x32_bf16 v[46:49], v[186:189], v[154:157], v[46:49]
	v_mfma_f32_16x16x32_bf16 v[42:45], v[186:189], v[162:165], v[42:45]
	v_mfma_f32_16x16x32_bf16 v[38:41], v[194:197], v[154:157], v[38:41]
	v_mfma_f32_16x16x32_bf16 v[34:37], v[194:197], v[162:165], v[34:37]
	v_mfma_f32_16x16x32_bf16 v[62:65], v[174:177], v[158:161], v[62:65]
	v_mfma_f32_16x16x32_bf16 v[58:61], v[174:177], v[166:169], v[58:61]
	v_mfma_f32_16x16x32_bf16 v[54:57], v[182:185], v[158:161], v[54:57]
	v_mfma_f32_16x16x32_bf16 v[50:53], v[182:185], v[166:169], v[50:53]
	v_mfma_f32_16x16x32_bf16 v[46:49], v[190:193], v[158:161], v[46:49]
	v_mfma_f32_16x16x32_bf16 v[42:45], v[190:193], v[166:169], v[42:45]
	v_mfma_f32_16x16x32_bf16 v[38:41], v[198:201], v[158:161], v[38:41]
	v_mfma_f32_16x16x32_bf16 v[34:37], v[198:201], v[166:169], v[34:37]
	s_barrier
; #define LDA(dst, b, h) _Pragma("unroll") for (int m = 0; m < 4; ++m) _Pragma("unroll") for (int k = 0; k < 2; ++k) \
;     dst[m][k] = *reinterpret_cast<const bf16x8*>((char*)SA(b, h) + lds_byte(wr * 64 + m * 16 + fr, k * 32 + fq * 8))
; #define LDB(dst, b, h) _Pragma("unroll") for (int n = 0; n < 2; ++n) _Pragma("unroll") for (int k = 0; k < 2; ++k) \
;     dst[n][k] = *reinterpret_cast<const bf16x8*>((char*)SB(b, h) + lds_byte(wc * 32 + n * 16 + fr, k * 32 + fq * 8))
; #define MMA(ai, bj, At_, Bt_) do { __builtin_amdgcn_s_setprio(1); \
;     _Pragma("unroll") for (int m = 0; m < 4; ++m) _Pragma("unroll") for (int n = 0; n < 2; ++n) _Pragma("unroll") for (int k = 0; k < 2; ++k) \
;       acc[ai][bj][m][n] = __builtin_amdgcn_mfma_f32_16x16x32_bf16(At_[m][k], Bt_[n][k], acc[ai][bj][m][n], 0, 0, 0); \
;     __builtin_amdgcn_s_setprio(0); } while (0)
; #define WAIT_V(n) asm volatile("s_waitcnt vmcnt(" #n ")" ::: "memory")
; #define WAIT_L(n) asm volatile("s_waitcnt lgkmcnt(" #n ")" ::: "memory")
; #define BAR __builtin_amdgcn_s_barrier()
; #define SCHED __builtin_amdgcn_sched_barrier(0)
; DI void gemm_tile(const GD& g, int pm, int pn, bf16_t* shm) {
;     ...
;     STAGE(SB(0, 1), Bt, ldb, bh1, t + 2);
;     WAIT_V(6); BAR; MMA(1, 1, At, B1); BAR;
;     LDB(B0, 1, 0); SCHED; LDA(At, 1, 0); STAGE(SA(0, 1), A, lda, brow + HALF, t + 2);
;     WAIT_L(8); BAR; WAIT_L(0); MMA(0, 0, At, B0); BAR; SCHED;
;     LDB(B1, 1, 1); STAGE(SB(1, 0), Bt, ldb, bh0, t + 3);
;     BAR; WAIT_L(0); MMA(0, 1, At, B1); BAR;
	s_add_u32 s82, s67, s54
	s_addc_u32 s83, s97, s55
	v_lshl_add_u64 v[154:155], s[82:83], 0, v[0:1]
	s_add_u32 s82, s67, s56
	s_mov_b32 m0, s69
	s_addc_u32 s83, s97, s57
	global_load_lds_dwordx4 v[154:155], off
	v_lshl_add_u64 v[154:155], s[82:83], 0, v[0:1]
	s_mov_b32 m0, s77
	s_nop 0
	global_load_lds_dwordx4 v[154:155], off
	s_waitcnt vmcnt(6)
	s_barrier
	v_mfma_f32_16x16x32_bf16 v[30:33], v[170:173], v[238:241], v[30:33]
	v_mfma_f32_16x16x32_bf16 v[26:29], v[170:173], v[246:249], v[26:29]
	v_mfma_f32_16x16x32_bf16 v[22:25], v[178:181], v[238:241], v[22:25]
	v_mfma_f32_16x16x32_bf16 v[18:21], v[178:181], v[246:249], v[18:21]
	v_mfma_f32_16x16x32_bf16 v[14:17], v[186:189], v[238:241], v[14:17]
	v_mfma_f32_16x16x32_bf16 v[10:13], v[186:189], v[246:249], v[10:13]
	v_mfma_f32_16x16x32_bf16 v[6:9], v[194:197], v[238:241], v[6:9]
	v_mfma_f32_16x16x32_bf16 v[2:5], v[194:197], v[246:249], v[2:5]
	v_mfma_f32_16x16x32_bf16 v[30:33], v[174:177], v[242:245], v[30:33]
	v_mfma_f32_16x16x32_bf16 v[26:29], v[174:177], v[214:217], v[26:29]
	v_mfma_f32_16x16x32_bf16 v[22:25], v[182:185], v[242:245], v[22:25]
	v_mfma_f32_16x16x32_bf16 v[18:21], v[182:185], v[214:217], v[18:21]
	v_mfma_f32_16x16x32_bf16 v[14:17], v[190:193], v[242:245], v[14:17]
	v_mfma_f32_16x16x32_bf16 v[10:13], v[190:193], v[214:217], v[10:13]
	v_mfma_f32_16x16x32_bf16 v[6:9], v[198:201], v[242:245], v[6:9]
	v_mfma_f32_16x16x32_bf16 v[2:5], v[198:201], v[214:217], v[2:5]
	s_barrier
	ds_read_b128 v[154:157], v152
	ds_read_b128 v[158:161], v152 offset:1024
	ds_read_b128 v[162:165], v152 offset:2048
	ds_read_b128 v[166:169], v152 offset:3072
	s_add_u32 s82, vcc_lo, s6
	s_addc_u32 s83, vcc_hi, s7
	v_lshl_add_u64 v[202:203], s[82:83], 0, v[0:1]
	s_add_u32 s82, vcc_lo, s8
	s_mov_b32 m0, s71
	s_addc_u32 s83, vcc_hi, s9
	ds_read_b128 v[170:173], v237 offset:32768
	ds_read_b128 v[174:177], v237 offset:33792
	ds_read_b128 v[178:181], v148 offset:32768
	ds_read_b128 v[182:185], v148 offset:33792
	ds_read_b128 v[186:189], v149 offset:32768
	ds_read_b128 v[190:193], v149 offset:33792
	ds_read_b128 v[194:197], v150 offset:32768
	ds_read_b128 v[198:201], v150 offset:33792
	global_load_lds_dwordx4 v[202:203], off
	v_lshl_add_u64 v[202:203], s[82:83], 0, v[0:1]
	s_mov_b32 m0, s65
	s_nop 0
	global_load_lds_dwordx4 v[202:203], off
	s_waitcnt lgkmcnt(8)
	s_barrier
	s_waitcnt lgkmcnt(0)
	v_mfma_f32_16x16x32_bf16 v[114:117], v[170:173], v[154:157], v[114:117]
	v_mfma_f32_16x16x32_bf16 v[126:129], v[170:173], v[162:165], v[126:129]
	v_mfma_f32_16x16x32_bf16 v[122:125], v[178:181], v[154:157], v[122:125]
	v_mfma_f32_16x16x32_bf16 v[118:121], v[178:181], v[162:165], v[118:121]
	v_mfma_f32_16x16x32_bf16 v[110:113], v[186:189], v[154:157], v[110:113]
	v_mfma_f32_16x16x32_bf16 v[106:109], v[186:189], v[162:165], v[106:109]
	v_mfma_f32_16x16x32_bf16 v[102:105], v[194:197], v[154:157], v[102:105]
	v_mfma_f32_16x16x32_bf16 v[98:101], v[194:197], v[162:165], v[98:101]
	v_mfma_f32_16x16x32_bf16 v[114:117], v[174:177], v[158:161], v[114:117]
	v_mfma_f32_16x16x32_bf16 v[126:129], v[174:177], v[166:169], v[126:129]
	v_mfma_f32_16x16x32_bf16 v[122:125], v[182:185], v[158:161], v[122:125]
	v_mfma_f32_16x16x32_bf16 v[118:121], v[182:185], v[166:169], v[118:121]
	v_mfma_f32_16x16x32_bf16 v[110:113], v[190:193], v[158:161], v[110:113]
	v_mfma_f32_16x16x32_bf16 v[106:109], v[190:193], v[166:169], v[106:109]
	v_mfma_f32_16x16x32_bf16 v[102:105], v[198:201], v[158:161], v[102:105]
	v_mfma_f32_16x16x32_bf16 v[98:101], v[198:201], v[166:169], v[98:101]
	s_barrier
	s_add_u32 s82, s58, s10
	s_addc_u32 s83, s59, s11
	v_lshl_add_u64 v[202:203], s[82:83], 0, v[0:1]
	s_add_u32 s82, s58, s12
	s_mov_b32 m0, s96
	s_addc_u32 s83, s59, s13
	ds_read_b128 v[214:217], v153
	ds_read_b128 v[238:241], v153 offset:1024
	ds_read_b128 v[242:245], v153 offset:2048
	ds_read_b128 v[246:249], v153 offset:3072
	global_load_lds_dwordx4 v[202:203], off
	v_lshl_add_u64 v[202:203], s[82:83], 0, v[0:1]
	s_mov_b32 m0, s60
	s_nop 0
	global_load_lds_dwordx4 v[202:203], off
	s_barrier
	s_waitcnt lgkmcnt(0)
	v_mfma_f32_16x16x32_bf16 v[94:97], v[170:173], v[214:217], v[94:97]
	v_mfma_f32_16x16x32_bf16 v[90:93], v[170:173], v[242:245], v[90:93]
	v_mfma_f32_16x16x32_bf16 v[86:89], v[178:181], v[214:217], v[86:89]
	v_mfma_f32_16x16x32_bf16 v[82:85], v[178:181], v[242:245], v[82:85]
	v_mfma_f32_16x16x32_bf16 v[78:81], v[186:189], v[214:217], v[78:81]
	v_mfma_f32_16x16x32_bf16 v[74:77], v[186:189], v[242:245], v[74:77]
	v_mfma_f32_16x16x32_bf16 v[70:73], v[194:197], v[214:217], v[70:73]
	v_mfma_f32_16x16x32_bf16 v[66:69], v[194:197], v[242:245], v[66:69]
	v_mfma_f32_16x16x32_bf16 v[94:97], v[174:177], v[238:241], v[94:97]
	v_mfma_f32_16x16x32_bf16 v[90:93], v[174:177], v[246:249], v[90:93]
	v_mfma_f32_16x16x32_bf16 v[86:89], v[182:185], v[238:241], v[86:89]
	v_mfma_f32_16x16x32_bf16 v[82:85], v[182:185], v[246:249], v[82:85]
	v_mfma_f32_16x16x32_bf16 v[78:81], v[190:193], v[238:241], v[78:81]
	v_mfma_f32_16x16x32_bf16 v[74:77], v[190:193], v[246:249], v[74:77]
	v_mfma_f32_16x16x32_bf16 v[70:73], v[198:201], v[238:241], v[70:73]
	v_mfma_f32_16x16x32_bf16 v[66:69], v[198:201], v[246:249], v[66:69]
	s_add_u32 s82, s41, s50
	s_addc_u32 s83, s63, s51
	v_lshl_add_u64 v[202:203], s[82:83], 0, v[0:1]
	s_add_u32 s82, s41, s52
	s_mov_b32 m0, s25
	s_addc_u32 s83, s63, s53
	s_barrier
	ds_read_b128 v[170:173], v237 offset:49152
	ds_read_b128 v[174:177], v237 offset:50176
	ds_read_b128 v[178:181], v148 offset:49152
	ds_read_b128 v[182:185], v148 offset:50176
	ds_read_b128 v[186:189], v149 offset:49152
	ds_read_b128 v[190:193], v149 offset:50176
	ds_read_b128 v[194:197], v150 offset:49152
	ds_read_b128 v[198:201], v150 offset:50176
	global_load_lds_dwordx4 v[202:203], off
	v_lshl_add_u64 v[202:203], s[82:83], 0, v[0:1]
	s_mov_b32 m0, s61
	s_nop 0
	global_load_lds_dwordx4 v[202:203], off
	s_barrier
; #define LDA(dst, b, h) _Pragma("unroll") for (int m = 0; m < 4; ++m) _Pragma("unroll") for (int k = 0; k < 2; ++k) \
;     dst[m][k] = *reinterpret_cast<const bf16x8*>((char*)SA(b, h) + lds_byte(wr * 64 + m * 16 + fr, k * 32 + fq * 8))
; #define LDB(dst, b, h) _Pragma("unroll") for (int n = 0; n < 2; ++n) _Pragma("unroll") for (int k = 0; k < 2; ++k) \
;     dst[n][k] = *reinterpret_cast<const bf16x8*>((char*)SB(b, h) + lds_byte(wc * 32 + n * 16 + fr, k * 32 + fq * 8))
; #define MMA(ai, bj, At_, Bt_) do { __builtin_amdgcn_s_setprio(1); \
;     _Pragma("unroll") for (int m = 0; m < 4; ++m) _Pragma("unroll") for (int n = 0; n < 2; ++n) _Pragma("unroll") for (int k = 0; k < 2; ++k) \
;       acc[ai][bj][m][n] = __builtin_amdgcn_mfma_f32_16x16x32_bf16(At_[m][k], Bt_[n][k], acc[ai][bj][m][n], 0, 0, 0); \
;     __builtin_amdgcn_s_setprio(0); } while (0)
; #define WAIT_V(n) asm volatile("s_waitcnt vmcnt(" #n ")" ::: "memory")
; #define WAIT_L(n) asm volatile("s_waitcnt lgkmcnt(" #n ")" ::: "memory")
; #define BAR __builtin_amdgcn_s_barrier()
; #define SCHED __builtin_amdgcn_sched_barrier(0)
; DI void gemm_tile(const GD& g, int pm, int pn, bf16_t* shm) {
;     ...
;     LDA(At, 1, 1); STAGE(SA(1, 0), A, lda, brow, t + 3);
;     BAR; WAIT_L(0); MMA(1, 0, At, B0); BAR; SCHED;
;     STAGE(SB(1, 1), Bt, ldb, bh1, t + 3);
;     WAIT_V(6); BAR; MMA(1, 1, At, B1); BAR;
;   }
;   { LDB(B0, 0, 0); LDA(At, 0, 0); STAGE(SA(1, 1), A, lda, brow + HALF, nt - 1);
;     BAR; WAIT_L(0); MMA(0, 0, At, B0); BAR;
;     LDB(B1, 0, 1); BAR; WAIT_L(0); MMA(0, 1, At, B1); BAR;
;     LDA(At, 0, 1); WAIT_V(4); BAR; WAIT_L(0); MMA(1, 0, At, B0); MMA(1, 1, At, B1); BAR; }
	s_waitcnt lgkmcnt(0)
	v_mfma_f32_16x16x32_bf16 v[62:65], v[170:173], v[154:157], v[62:65]
	v_mfma_f32_16x16x32_bf16 v[58:61], v[170:173], v[162:165], v[58:61]
	v_mfma_f32_16x16x32_bf16 v[54:57], v[178:181], v[154:157], v[54:57]
	v_mfma_f32_16x16x32_bf16 v[50:53], v[178:181], v[162:165], v[50:53]
	v_mfma_f32_16x16x32_bf16 v[46:49], v[186:189], v[154:157], v[46:49]
	v_mfma_f32_16x16x32_bf16 v[42:45], v[186:189], v[162:165], v[42:45]
	v_mfma_f32_16x16x32_bf16 v[38:41], v[194:197], v[154:157], v[38:41]
	v_mfma_f32_16x16x32_bf16 v[34:37], v[194:197], v[162:165], v[34:37]
	v_mfma_f32_16x16x32_bf16 v[62:65], v[174:177], v[158:161], v[62:65]
	v_mfma_f32_16x16x32_bf16 v[58:61], v[174:177], v[166:169], v[58:61]
	v_mfma_f32_16x16x32_bf16 v[54:57], v[182:185], v[158:161], v[54:57]
	v_mfma_f32_16x16x32_bf16 v[50:53], v[182:185], v[166:169], v[50:53]
	v_mfma_f32_16x16x32_bf16 v[46:49], v[190:193], v[158:161], v[46:49]
	v_mfma_f32_16x16x32_bf16 v[42:45], v[190:193], v[166:169], v[42:45]
	v_mfma_f32_16x16x32_bf16 v[38:41], v[198:201], v[158:161], v[38:41]
	v_mfma_f32_16x16x32_bf16 v[34:37], v[198:201], v[166:169], v[34:37]
	s_barrier
	s_add_u32 s82, s58, s54
	s_addc_u32 s83, s59, s55
	v_lshl_add_u64 v[154:155], s[82:83], 0, v[0:1]
	s_add_u32 s82, s58, s56
	s_mov_b32 m0, s62
	s_addc_u32 s83, s59, s57
	global_load_lds_dwordx4 v[154:155], off
	v_lshl_add_u64 v[154:155], s[82:83], 0, v[0:1]
	s_mov_b32 m0, s40
	s_nop 0
	global_load_lds_dwordx4 v[154:155], off
	s_waitcnt vmcnt(6)
	s_barrier
	v_mfma_f32_16x16x32_bf16 v[30:33], v[170:173], v[214:217], v[30:33]
	v_mfma_f32_16x16x32_bf16 v[26:29], v[170:173], v[242:245], v[26:29]
	v_mfma_f32_16x16x32_bf16 v[22:25], v[178:181], v[214:217], v[22:25]
	v_mfma_f32_16x16x32_bf16 v[18:21], v[178:181], v[242:245], v[18:21]
	v_mfma_f32_16x16x32_bf16 v[14:17], v[186:189], v[214:217], v[14:17]
	v_mfma_f32_16x16x32_bf16 v[10:13], v[186:189], v[242:245], v[10:13]
	v_mfma_f32_16x16x32_bf16 v[6:9], v[194:197], v[214:217], v[6:9]
	v_mfma_f32_16x16x32_bf16 v[2:5], v[194:197], v[242:245], v[2:5]
	v_mfma_f32_16x16x32_bf16 v[30:33], v[174:177], v[238:241], v[30:33]
	v_mfma_f32_16x16x32_bf16 v[26:29], v[174:177], v[246:249], v[26:29]
	v_mfma_f32_16x16x32_bf16 v[22:25], v[182:185], v[238:241], v[22:25]
	v_mfma_f32_16x16x32_bf16 v[18:21], v[182:185], v[246:249], v[18:21]
	v_mfma_f32_16x16x32_bf16 v[14:17], v[190:193], v[238:241], v[14:17]
	v_mfma_f32_16x16x32_bf16 v[10:13], v[190:193], v[246:249], v[10:13]
	v_mfma_f32_16x16x32_bf16 v[6:9], v[198:201], v[238:241], v[6:9]
	v_mfma_f32_16x16x32_bf16 v[2:5], v[198:201], v[246:249], v[2:5]
	s_add_u32 s58, s58, 0x100
	s_addc_u32 s59, s59, 0
	s_add_u32 s41, s41, 0x100
	s_addc_u32 s63, s63, 0
	s_cmp_lt_u32 s3, s2
	s_barrier
	s_cbranch_scc1 .LBB0_460
	v_mov_b32_e32 v146, v143
	v_mov_b32_e32 v147, v144
	v_mov_b32_e32 v148, v145
	v_mov_b32_e32 v149, v142
.LBB0_462:
	v_readlane_b32 s56, v253, 39
	v_readlane_b32 s57, v253, 40
	s_add_i32 s56, s24, -1
	s_lshl_b64 s[2:3], s[56:57], 7
	s_add_u32 s2, s0, s2
	v_add_u32_e32 v142, v141, v131
	v_add_u32_e32 v150, v141, v146
	v_add_u32_e32 v154, v141, v147
	v_add_u32_e32 v141, v141, v148
	s_addc_u32 s3, s1, s3
	ds_read_b128 v[142:145], v142
	ds_read_b128 v[150:153], v150
	ds_read_b128 v[154:157], v154
	ds_read_b128 v[158:161], v141
	v_add_u32_e32 v141, 0, v133
	s_add_u32 s0, s2, s6
	v_add_u32_e32 v203, v141, v134
	v_add_u32_e32 v134, 0, v133
	s_addc_u32 s1, s3, s7
	s_add_i32 m0, s70, 0xc000
	v_add_u32_e32 v214, v134, v135
	v_add_u32_e32 v215, v134, v136
	v_add_u32_e32 v134, 0, v133
	v_add_u32_e32 v133, 0, v133
	v_lshl_add_u64 v[186:187], s[0:1], 0, v[0:1]
	s_add_u32 s0, s2, s8
	v_add_u32_e32 v202, v141, v149
	v_add_u32_e32 v216, v134, v137
	v_add_u32_e32 v237, v133, v139
	s_addc_u32 s1, s3, s9
	ds_read_b128 v[162:165], v202
	ds_read_b128 v[166:169], v203
	ds_read_b128 v[170:173], v214
	ds_read_b128 v[174:177], v215
	v_add_u32_e32 v217, v134, v138
	ds_read_b128 v[134:137], v216
	ds_read_b128 v[178:181], v217
	v_add_u32_e32 v133, v133, v140
	ds_read_b128 v[138:141], v237
	ds_read_b128 v[182:185], v133
	global_load_lds_dwordx4 v[186:187], off
	v_lshl_add_u64 v[186:187], s[0:1], 0, v[0:1]
	s_add_i32 m0, s70, 0xe000
	s_nop 0
	global_load_lds_dwordx4 v[186:187], off
	s_barrier
	s_waitcnt lgkmcnt(0)
	v_mfma_f32_16x16x32_bf16 v[114:117], v[162:165], v[142:145], v[114:117]
	v_mfma_f32_16x16x32_bf16 v[110:113], v[134:137], v[142:145], v[110:113]
	v_mfma_f32_16x16x32_bf16 v[106:109], v[134:137], v[154:157], v[106:109]
	v_mfma_f32_16x16x32_bf16 v[102:105], v[138:141], v[142:145], v[102:105]
	v_mfma_f32_16x16x32_bf16 v[98:101], v[138:141], v[154:157], v[98:101]
	v_mfma_f32_16x16x32_bf16 v[114:117], v[166:169], v[150:153], v[114:117]
	v_mfma_f32_16x16x32_bf16 v[126:129], v[162:165], v[154:157], v[126:129]
	v_mfma_f32_16x16x32_bf16 v[122:125], v[170:173], v[142:145], v[122:125]
	v_mfma_f32_16x16x32_bf16 v[118:121], v[170:173], v[154:157], v[118:121]
	v_mfma_f32_16x16x32_bf16 v[110:113], v[178:181], v[150:153], v[110:113]
	v_mfma_f32_16x16x32_bf16 v[106:109], v[178:181], v[158:161], v[106:109]
	v_mfma_f32_16x16x32_bf16 v[102:105], v[182:185], v[150:153], v[102:105]
	v_mfma_f32_16x16x32_bf16 v[98:101], v[182:185], v[158:161], v[98:101]
	v_mfma_f32_16x16x32_bf16 v[186:189], v[166:169], v[158:161], v[126:129]
	v_mfma_f32_16x16x32_bf16 v[190:193], v[174:177], v[150:153], v[122:125]
	v_mfma_f32_16x16x32_bf16 v[194:197], v[174:177], v[158:161], v[118:121]
	s_add_i32 s0, 0, 0x14000
	v_add_u32_e32 v0, s0, v132
	v_add_u32_e32 v118, v0, v131
	v_add_u32_e32 v122, v0, v146
	v_add_u32_e32 v126, v0, v147
	s_barrier
; #define LDA(dst, b, h) _Pragma("unroll") for (int m = 0; m < 4; ++m) _Pragma("unroll") for (int k = 0; k < 2; ++k) \
;     dst[m][k] = *reinterpret_cast<const bf16x8*>((char*)SA(b, h) + lds_byte(wr * 64 + m * 16 + fr, k * 32 + fq * 8))
; #define LDB(dst, b, h) _Pragma("unroll") for (int n = 0; n < 2; ++n) _Pragma("unroll") for (int k = 0; k < 2; ++k) \
;     dst[n][k] = *reinterpret_cast<const bf16x8*>((char*)SB(b, h) + lds_byte(wc * 32 + n * 16 + fr, k * 32 + fq * 8))
; #define MMA(ai, bj, At_, Bt_) do { __builtin_amdgcn_s_setprio(1); \
;     _Pragma("unroll") for (int m = 0; m < 4; ++m) _Pragma("unroll") for (int n = 0; n < 2; ++n) _Pragma("unroll") for (int k = 0; k < 2; ++k) \
;       acc[ai][bj][m][n] = __builtin_amdgcn_mfma_f32_16x16x32_bf16(At_[m][k], Bt_[n][k], acc[ai][bj][m][n], 0, 0, 0); \
;     __builtin_amdgcn_s_setprio(0); } while (0)
; #define WAIT_V(n) asm volatile("s_waitcnt vmcnt(" #n ")" ::: "memory")
; #define WAIT_L(n) asm volatile("s_waitcnt lgkmcnt(" #n ")" ::: "memory")
; #define BAR __builtin_amdgcn_s_barrier()
; DI void gemm_tile(const GD& g, int pm, int pn, bf16_t* shm) {
;     ...
;     BAR; WAIT_L(0); MMA(0, 0, At, B0); BAR;
;     LDB(B1, 0, 1); BAR; WAIT_L(0); MMA(0, 1, At, B1); BAR;
;     LDA(At, 0, 1); WAIT_V(4); BAR; WAIT_L(0); MMA(1, 0, At, B0); MMA(1, 1, At, B1); BAR; }
;   { LDB(B0, 1, 0); LDA(At, 1, 0); WAIT_V(2); BAR; WAIT_L(0); MMA(0, 0, At, B0); BAR;
;     LDB(B1, 1, 1); WAIT_V(0); BAR; WAIT_L(0); MMA(0, 1, At, B1); BAR;
	ds_read_b128 v[118:121], v118
	ds_read_b128 v[122:125], v122
	v_add_u32_e32 v0, v0, v148
	ds_read_b128 v[126:129], v126
	ds_read_b128 v[198:201], v0
	s_barrier
	s_waitcnt lgkmcnt(0)
	v_mfma_f32_16x16x32_bf16 v[94:97], v[162:165], v[118:121], v[94:97]
	v_mfma_f32_16x16x32_bf16 v[90:93], v[162:165], v[126:129], v[90:93]
	v_mfma_f32_16x16x32_bf16 v[86:89], v[170:173], v[118:121], v[86:89]
	v_mfma_f32_16x16x32_bf16 v[82:85], v[170:173], v[126:129], v[82:85]
	v_mfma_f32_16x16x32_bf16 v[78:81], v[134:137], v[118:121], v[78:81]
	v_mfma_f32_16x16x32_bf16 v[74:77], v[134:137], v[126:129], v[74:77]
	v_mfma_f32_16x16x32_bf16 v[70:73], v[138:141], v[118:121], v[70:73]
	v_mfma_f32_16x16x32_bf16 v[66:69], v[138:141], v[126:129], v[66:69]
	v_mfma_f32_16x16x32_bf16 v[94:97], v[166:169], v[122:125], v[94:97]
	v_mfma_f32_16x16x32_bf16 v[90:93], v[166:169], v[198:201], v[90:93]
	v_mfma_f32_16x16x32_bf16 v[86:89], v[174:177], v[122:125], v[86:89]
	v_mfma_f32_16x16x32_bf16 v[82:85], v[174:177], v[198:201], v[82:85]
	v_mfma_f32_16x16x32_bf16 v[78:81], v[178:181], v[122:125], v[78:81]
	v_mfma_f32_16x16x32_bf16 v[74:77], v[178:181], v[198:201], v[74:77]
	v_mfma_f32_16x16x32_bf16 v[70:73], v[182:185], v[122:125], v[70:73]
	v_mfma_f32_16x16x32_bf16 v[66:69], v[182:185], v[198:201], v[66:69]
	s_barrier
	ds_read_b128 v[134:137], v202 offset:16384
	ds_read_b128 v[138:141], v203 offset:16384
	ds_read_b128 v[162:165], v214 offset:16384
	ds_read_b128 v[166:169], v215 offset:16384
	ds_read_b128 v[170:173], v216 offset:16384
	ds_read_b128 v[174:177], v217 offset:16384
	ds_read_b128 v[178:181], v237 offset:16384
	ds_read_b128 v[182:185], v133 offset:16384
	s_waitcnt vmcnt(4)
	s_barrier
	s_waitcnt lgkmcnt(0)
	v_mfma_f32_16x16x32_bf16 v[62:65], v[134:137], v[142:145], v[62:65]
	v_mfma_f32_16x16x32_bf16 v[58:61], v[134:137], v[154:157], v[58:61]
	v_mfma_f32_16x16x32_bf16 v[54:57], v[162:165], v[142:145], v[54:57]
	v_mfma_f32_16x16x32_bf16 v[50:53], v[162:165], v[154:157], v[50:53]
	v_mfma_f32_16x16x32_bf16 v[46:49], v[170:173], v[142:145], v[46:49]
	v_mfma_f32_16x16x32_bf16 v[42:45], v[170:173], v[154:157], v[42:45]
	v_mfma_f32_16x16x32_bf16 v[38:41], v[178:181], v[142:145], v[38:41]
	v_mfma_f32_16x16x32_bf16 v[34:37], v[178:181], v[154:157], v[34:37]
	v_mfma_f32_16x16x32_bf16 v[62:65], v[138:141], v[150:153], v[62:65]
	v_mfma_f32_16x16x32_bf16 v[58:61], v[138:141], v[158:161], v[58:61]
	v_mfma_f32_16x16x32_bf16 v[54:57], v[166:169], v[150:153], v[54:57]
	v_mfma_f32_16x16x32_bf16 v[50:53], v[166:169], v[158:161], v[50:53]
	v_mfma_f32_16x16x32_bf16 v[46:49], v[174:177], v[150:153], v[46:49]
	v_mfma_f32_16x16x32_bf16 v[42:45], v[174:177], v[158:161], v[42:45]
	v_mfma_f32_16x16x32_bf16 v[38:41], v[182:185], v[150:153], v[38:41]
	v_mfma_f32_16x16x32_bf16 v[34:37], v[182:185], v[158:161], v[34:37]
	v_mfma_f32_16x16x32_bf16 v[30:33], v[134:137], v[118:121], v[30:33]
	v_mfma_f32_16x16x32_bf16 v[26:29], v[134:137], v[126:129], v[26:29]
	v_mfma_f32_16x16x32_bf16 v[22:25], v[162:165], v[118:121], v[22:25]
	v_mfma_f32_16x16x32_bf16 v[18:21], v[162:165], v[126:129], v[18:21]
	v_mfma_f32_16x16x32_bf16 v[30:33], v[138:141], v[122:125], v[30:33]
	v_mfma_f32_16x16x32_bf16 v[26:29], v[138:141], v[198:201], v[26:29]
	v_mfma_f32_16x16x32_bf16 v[22:25], v[166:169], v[122:125], v[22:25]
	v_mfma_f32_16x16x32_bf16 v[18:21], v[166:169], v[198:201], v[18:21]
	v_mfma_f32_16x16x32_bf16 v[14:17], v[170:173], v[118:121], v[14:17]
	v_mfma_f32_16x16x32_bf16 v[10:13], v[170:173], v[126:129], v[10:13]
	v_mfma_f32_16x16x32_bf16 v[6:9], v[178:181], v[118:121], v[6:9]
	v_mfma_f32_16x16x32_bf16 v[2:5], v[178:181], v[126:129], v[2:5]
	v_mfma_f32_16x16x32_bf16 v[134:137], v[174:177], v[122:125], v[14:17]
	v_mfma_f32_16x16x32_bf16 v[138:141], v[174:177], v[198:201], v[10:13]
	v_mfma_f32_16x16x32_bf16 v[142:145], v[182:185], v[122:125], v[6:9]
	v_mfma_f32_16x16x32_bf16 v[150:153], v[182:185], v[198:201], v[2:5]
	s_add_i32 s0, 0, 0x18000
	v_add_u32_e32 v0, s0, v132
	s_nop 0
	v_add_u32_e32 v2, v0, v131
	s_barrier
	v_add_u32_e32 v3, v0, v146
	ds_read_b128 v[154:157], v2
	ds_read_b128 v[158:161], v3
	v_add_u32_e32 v2, v0, v147
	v_add_u32_e32 v0, v0, v148
	ds_read_b128 v[162:165], v2
	ds_read_b128 v[166:169], v0
	ds_read_b128 v[2:5], v202 offset:32768
	ds_read_b128 v[6:9], v203 offset:32768
	ds_read_b128 v[10:13], v214 offset:32768
	ds_read_b128 v[14:17], v215 offset:32768
	ds_read_b128 v[170:173], v216 offset:32768
	ds_read_b128 v[174:177], v217 offset:32768
	ds_read_b128 v[178:181], v237 offset:32768
	ds_read_b128 v[182:185], v133 offset:32768
	s_waitcnt vmcnt(2)
	s_barrier
; #define LDA(dst, b, h) _Pragma("unroll") for (int m = 0; m < 4; ++m) _Pragma("unroll") for (int k = 0; k < 2; ++k) \
;     dst[m][k] = *reinterpret_cast<const bf16x8*>((char*)SA(b, h) + lds_byte(wr * 64 + m * 16 + fr, k * 32 + fq * 8))
; #define LDB(dst, b, h) _Pragma("unroll") for (int n = 0; n < 2; ++n) _Pragma("unroll") for (int k = 0; k < 2; ++k) \
;     dst[n][k] = *reinterpret_cast<const bf16x8*>((char*)SB(b, h) + lds_byte(wc * 32 + n * 16 + fr, k * 32 + fq * 8))
; #define MMA(ai, bj, At_, Bt_) do { __builtin_amdgcn_s_setprio(1); \
;     _Pragma("unroll") for (int m = 0; m < 4; ++m) _Pragma("unroll") for (int n = 0; n < 2; ++n) _Pragma("unroll") for (int k = 0; k < 2; ++k) \
;       acc[ai][bj][m][n] = __builtin_amdgcn_mfma_f32_16x16x32_bf16(At_[m][k], Bt_[n][k], acc[ai][bj][m][n], 0, 0, 0); \
;     __builtin_amdgcn_s_setprio(0); } while (0)
; #define WAIT_V(n) asm volatile("s_waitcnt vmcnt(" #n ")" ::: "memory")
; #define WAIT_L(n) asm volatile("s_waitcnt lgkmcnt(" #n ")" ::: "memory")
; #define BAR __builtin_amdgcn_s_barrier()
; DI void gemm_tile(const GD& g, int pm, int pn, bf16_t* shm) {
;     ...
;   { LDB(B0, 1, 0); LDA(At, 1, 0); WAIT_V(2); BAR; WAIT_L(0); MMA(0, 0, At, B0); BAR;
;     LDB(B1, 1, 1); WAIT_V(0); BAR; WAIT_L(0); MMA(0, 1, At, B1); BAR;
;     LDA(At, 1, 1); BAR; WAIT_L(0); MMA(1, 0, At, B0); MMA(1, 1, At, B1); BAR; }
;   if (wr == 0) BAR;
;   __syncthreads();
	s_waitcnt lgkmcnt(0)
	v_mfma_f32_16x16x32_bf16 v[114:117], v[2:5], v[154:157], v[114:117]
	v_mfma_f32_16x16x32_bf16 v[126:129], v[6:9], v[158:161], v[114:117]
	v_mfma_f32_16x16x32_bf16 v[114:117], v[2:5], v[162:165], v[186:189]
	v_mfma_f32_16x16x32_bf16 v[122:125], v[6:9], v[166:169], v[114:117]
	v_mfma_f32_16x16x32_bf16 v[114:117], v[10:13], v[154:157], v[190:193]
	v_mfma_f32_16x16x32_bf16 v[118:121], v[14:17], v[158:161], v[114:117]
	v_mfma_f32_16x16x32_bf16 v[114:117], v[10:13], v[162:165], v[194:197]
	v_mfma_f32_16x16x32_bf16 v[110:113], v[170:173], v[154:157], v[110:113]
	v_mfma_f32_16x16x32_bf16 v[106:109], v[170:173], v[162:165], v[106:109]
	v_mfma_f32_16x16x32_bf16 v[102:105], v[178:181], v[154:157], v[102:105]
	v_mfma_f32_16x16x32_bf16 v[98:101], v[178:181], v[162:165], v[98:101]
	v_mfma_f32_16x16x32_bf16 v[114:117], v[14:17], v[166:169], v[114:117]
	v_mfma_f32_16x16x32_bf16 v[110:113], v[174:177], v[158:161], v[110:113]
	v_mfma_f32_16x16x32_bf16 v[106:109], v[174:177], v[166:169], v[106:109]
	v_mfma_f32_16x16x32_bf16 v[102:105], v[182:185], v[158:161], v[102:105]
	v_mfma_f32_16x16x32_bf16 v[98:101], v[182:185], v[166:169], v[98:101]
	s_add_i32 s0, 0, 0x1c000
	v_add_u32_e32 v0, s0, v132
	v_add_u32_e32 v131, v0, v131
	s_barrier
	v_add_u32_e32 v132, v0, v146
	ds_read_b128 v[186:189], v131
	ds_read_b128 v[190:193], v132
	v_add_u32_e32 v131, v0, v147
	v_add_u32_e32 v0, v0, v148
	ds_read_b128 v[146:149], v131
	ds_read_b128 v[194:197], v0
	s_waitcnt vmcnt(0)
	s_barrier
	s_waitcnt lgkmcnt(0)
	v_mfma_f32_16x16x32_bf16 v[94:97], v[2:5], v[186:189], v[94:97]
	v_mfma_f32_16x16x32_bf16 v[2:5], v[2:5], v[146:149], v[90:93]
	v_mfma_f32_16x16x32_bf16 v[90:93], v[6:9], v[194:197], v[2:5]
	v_mfma_f32_16x16x32_bf16 v[2:5], v[10:13], v[186:189], v[86:89]
	v_mfma_f32_16x16x32_bf16 v[86:89], v[14:17], v[190:193], v[2:5]
	v_mfma_f32_16x16x32_bf16 v[2:5], v[10:13], v[146:149], v[82:85]
	v_mfma_f32_16x16x32_bf16 v[82:85], v[14:17], v[194:197], v[2:5]
	v_mfma_f32_16x16x32_bf16 v[2:5], v[170:173], v[186:189], v[78:81]
	v_mfma_f32_16x16x32_bf16 v[14:17], v[174:177], v[190:193], v[2:5]
	v_mfma_f32_16x16x32_bf16 v[2:5], v[170:173], v[146:149], v[74:77]
	v_mfma_f32_16x16x32_bf16 v[10:13], v[174:177], v[194:197], v[2:5]
	v_mfma_f32_16x16x32_bf16 v[2:5], v[178:181], v[186:189], v[70:73]
	v_mfma_f32_16x16x32_bf16 v[94:97], v[6:9], v[190:193], v[94:97]
	v_mfma_f32_16x16x32_bf16 v[6:9], v[182:185], v[190:193], v[2:5]
	v_mfma_f32_16x16x32_bf16 v[2:5], v[178:181], v[146:149], v[66:69]
	v_mfma_f32_16x16x32_bf16 v[2:5], v[182:185], v[194:197], v[2:5]
	s_barrier
	ds_read_b128 v[170:173], v202 offset:49152
	ds_read_b128 v[174:177], v203 offset:49152
	ds_read_b128 v[178:181], v214 offset:49152
	ds_read_b128 v[182:185], v215 offset:49152
	ds_read_b128 v[198:201], v216 offset:49152
	ds_read_b128 v[214:217], v217 offset:49152
	ds_read_b128 v[238:241], v237 offset:49152
	ds_read_b128 v[242:245], v133 offset:49152
	s_barrier
	s_waitcnt lgkmcnt(0)
	v_mfma_f32_16x16x32_bf16 v[62:65], v[170:173], v[154:157], v[62:65]
	v_mfma_f32_16x16x32_bf16 v[58:61], v[170:173], v[162:165], v[58:61]
	v_mfma_f32_16x16x32_bf16 v[54:57], v[178:181], v[154:157], v[54:57]
	v_mfma_f32_16x16x32_bf16 v[50:53], v[178:181], v[162:165], v[50:53]
	v_mfma_f32_16x16x32_bf16 v[46:49], v[198:201], v[154:157], v[46:49]
	v_mfma_f32_16x16x32_bf16 v[42:45], v[198:201], v[162:165], v[42:45]
	v_mfma_f32_16x16x32_bf16 v[38:41], v[238:241], v[154:157], v[38:41]
	v_mfma_f32_16x16x32_bf16 v[34:37], v[238:241], v[162:165], v[34:37]
	v_mfma_f32_16x16x32_bf16 v[78:81], v[174:177], v[158:161], v[62:65]
	v_mfma_f32_16x16x32_bf16 v[74:77], v[174:177], v[166:169], v[58:61]
	v_mfma_f32_16x16x32_bf16 v[70:73], v[182:185], v[158:161], v[54:57]
	v_mfma_f32_16x16x32_bf16 v[66:69], v[182:185], v[166:169], v[50:53]
	v_mfma_f32_16x16x32_bf16 v[62:65], v[214:217], v[158:161], v[46:49]
	v_mfma_f32_16x16x32_bf16 v[58:61], v[214:217], v[166:169], v[42:45]
	v_mfma_f32_16x16x32_bf16 v[54:57], v[242:245], v[158:161], v[38:41]
	v_mfma_f32_16x16x32_bf16 v[50:53], v[242:245], v[166:169], v[34:37]
	v_mfma_f32_16x16x32_bf16 v[18:21], v[178:181], v[146:149], v[18:21]
	v_mfma_f32_16x16x32_bf16 v[30:33], v[170:173], v[186:189], v[30:33]
	v_mfma_f32_16x16x32_bf16 v[34:37], v[182:185], v[194:197], v[18:21]
	v_mfma_f32_16x16x32_bf16 v[18:21], v[198:201], v[186:189], v[134:137]
	v_mfma_f32_16x16x32_bf16 v[46:49], v[174:177], v[190:193], v[30:33]
	v_mfma_f32_16x16x32_bf16 v[26:29], v[170:173], v[146:149], v[26:29]
	v_mfma_f32_16x16x32_bf16 v[30:33], v[214:217], v[190:193], v[18:21]
	v_mfma_f32_16x16x32_bf16 v[18:21], v[198:201], v[146:149], v[138:141]
	v_mfma_f32_16x16x32_bf16 v[42:45], v[174:177], v[194:197], v[26:29]
	v_mfma_f32_16x16x32_bf16 v[22:25], v[178:181], v[186:189], v[22:25]
	v_mfma_f32_16x16x32_bf16 v[26:29], v[214:217], v[194:197], v[18:21]
	v_mfma_f32_16x16x32_bf16 v[18:21], v[238:241], v[186:189], v[142:145]
	v_mfma_f32_16x16x32_bf16 v[38:41], v[182:185], v[190:193], v[22:25]
	v_mfma_f32_16x16x32_bf16 v[22:25], v[242:245], v[190:193], v[18:21]
	v_mfma_f32_16x16x32_bf16 v[18:21], v[238:241], v[146:149], v[150:153]
	v_mfma_f32_16x16x32_bf16 v[18:21], v[242:245], v[194:197], v[18:21]
	s_setprio 0
	s_movk_i32 s0, 0x100
	v_cmp_gt_u32_e32 vcc, s0, v130
	s_barrier
	s_and_saveexec_b64 s[0:1], vcc
	s_mov_b32 s96, s68
	s_mov_b32 s36, s89
	s_cbranch_execz .LBB0_464
	s_barrier
